# split conversion schedule guarded on the 512-block grid (generic fallback otherwise); otherwise identical to previous best
# speedup vs baseline: 1.1410x; 1.0004x over previous
.LBB0_21:
	v_readlane_b32 s6, v244, 1
	v_readlane_b32 s7, v244, 2
	s_cmp_lt_u32 s70, 11
	v_readlane_b32 s0, v244, 3
	s_mov_b32 s71, s6
	s_cselect_b64 s[6:7], -1, 0
	s_add_i32 s20, s70, -9
	v_readlane_b32 s1, v244, 4
	v_readlane_b32 s3, v244, 0
	s_cmp_gt_u32 s70, 10
	s_cselect_b64 s[22:23], -1, 0
	s_waitcnt lgkmcnt(0)
	s_load_dwordx2 s[24:25], s[0:1], 0xb8
	s_and_b64 s[18:19], s[22:23], exec
	s_cselect_b32 s18, s20, s70
	s_cmp_lt_u32 s70, 2
	s_cselect_b32 s19, s70, s18
	s_cmp_eq_u32 s70, 5
	s_cbranch_scc0 .Lhk_no
	s_cmpk_eq_u32 s71, 0x200
	s_cbranch_scc0 .Lhk_no
	s_cmpk_lt_u32 s3, 0x100
	s_cbranch_scc1 .Lhk_no
	s_waitcnt lgkmcnt(0)
	s_branch .Lcv_s5y

.Lbar_cv:
	v_readlane_b32 s3, v244, 0
	v_readlane_b32 s0, v244, 3
	v_readlane_b32 s1, v244, 4
	v_readlane_b32 s71, v244, 1
	s_nop 3
	s_cmpk_eq_u32 s71, 0x200
	s_cbranch_scc0 .Lbar_go
	s_cmpk_lt_u32 s3, 0x100
	s_cbranch_scc0 .Lbar_go
	s_waitcnt vmcnt(0) lgkmcnt(0)
	s_barrier
	s_branch .Lcv_s5o

.Lmd_nob:
	s_lshl_b32 s37, s26, 2
	s_add_i32 s37, s37, s51
	s_mul_i32 s37, s37, 0x6000
	s_add_i32 s37, s37, s43
	s_mul_i32 s43, s28, 0x30000
	s_add_i32 s37, s37, s43
	s_add_u32 s56, s56, s37
	s_addc_u32 s57, s57, 0
	s_waitcnt lgkmcnt(0)
	v_add_f32_e32 v2, v2, v6
	v_add_f32_e32 v10, v10, v14
	v_add_f32_e32 v3, v3, v7
	v_add_f32_e32 v11, v11, v15
	v_add_f32_e32 v4, v4, v8
	v_add_f32_e32 v12, v12, v16
	v_add_f32_e32 v5, v5, v9
	v_add_f32_e32 v13, v13, v17
	v_add_f32_e32 v2, v2, v10
	v_add_f32_e32 v3, v3, v11
	v_add_f32_e32 v4, v4, v12
	v_add_f32_e32 v5, v5, v13
	s_waitcnt vmcnt(0)
	v_add_f32_e32 v2, v2, v136
	v_add_f32_e32 v3, v3, v137
	v_add_f32_e32 v4, v4, v138
	v_add_f32_e32 v5, v5, v139
	global_store_dwordx4 v131, v[2:5], s[56:57]
	s_barrier
	v_mov_b32_e32 v98, 0x4800
	v_mov_b32_e32 v100, 0x4804
	v_mov_b32_e32 v102, 0x4808
	v_mov_b32_e32 v104, 0x480c
	s_cmpk_eq_u32 s71, 0x200
	s_cbranch_scc0 .Lcv_p0b
	s_branch .LBB0_435
.Lcv_p0a:
	s_mov_b32 s28, 0
	s_add_i32 s26, s3, 0xffffff40
	s_add_i32 s27, s71, 0xffffff40
	s_cmpk_eq_u32 s71, 0x200
	s_cbranch_scc1 .Lcv_p0a_s
	s_mov_b32 s29, 0
	s_lshl_b32 s89, s27, 3
	s_branch .Lcv_go
.Lcv_p0a_s:
	s_mov_b32 s29, 2
	s_movk_i32 s89, 0x780
	s_branch .Lcv_go

.Lcv_p10:
	s_mov_b32 s28, 1
	s_mov_b32 s29, 1
	s_mov_b32 s26, s3
	s_cmpk_eq_u32 s71, 0x200
	s_cbranch_scc0 .Lcv_p10_g
	s_add_i32 s26, s3, 0x1e0
.Lcv_p10_g:
	s_mov_b32 s27, s71
	s_movk_i32 s89, 0x1a00
	s_branch .Lcv_go
